# v16 + all three mixer B gate loads hoisted + MLA next-tile loads issued before the tile barrier + attention packed-fp32 ops split (combination of earlier individually-neutral edits)
# baseline (speedup 1.0000x reference)
.LBB0_1240:
	v_add_u32_e32 v0, 0x21300, v200
	ds_read_b32 v0, v0
	v_lshlrev_b64 v[72:73], 12, v[132:133]
	v_mov_b32_e32 v44, v35
	v_mov_b32_e32 v35, v47
	v_lshl_add_u64 v[46:47], s[24:25], 0, v[72:73]
	s_mov_b32 s73, s67
	v_ashrrev_i32_e32 v131, 31, v130
	v_lshl_add_u64 v[46:47], v[46:47], 0, s[72:73]
	s_mov_b64 s[8:9], 0x11c98800
	v_lshl_add_u64 v[46:47], v[130:131], 1, v[46:47]
	v_mov_b32_e32 v41, v51
	v_mov_b32_e32 v71, v52
	v_pk_mov_b32 v[50:51], v[52:53], v[50:51] op_sel:[1,0]
	v_lshl_add_u64 v[52:53], v[46:47], 0, s[8:9]
	s_mov_b32 s7, 0x11c98000
	ds_read2st64_b32 v[56:57], v200 offset0:168 offset1:176
	ds_read2st64_b32 v[58:59], v199 offset0:128 offset1:136
	ds_read2st64_b32 v[60:61], v200 offset0:184 offset1:192
	ds_read2st64_b32 v[62:63], v199 offset0:144 offset1:152
	ds_read2st64_b32 v[64:65], v200 offset0:200 offset1:208
	ds_read2st64_b32 v[66:67], v199 offset0:160 offset1:168
	ds_read2st64_b32 v[68:69], v200 offset0:216 offset1:224
	ds_read_b32 v70, v199 offset:45056
	s_waitcnt vmcnt(0) lgkmcnt(8)
	v_lshlrev_b32_e32 v0, 16, v0
	v_mul_f32_e32 v0, 0xbfb8aa3b, v0
	v_exp_f32_e32 v0, v0
	s_nop 0
	v_add_f32_e32 v0, 1.0, v0
	v_div_scale_f32 v55, s[10:11], v0, v0, 1.0
	v_rcp_f32_e32 v72, v55
	v_div_scale_f32 v73, vcc, 1.0, v0, 1.0
	v_fma_f32 v74, -v55, v72, 1.0
	v_fmac_f32_e32 v72, v74, v72
	v_mul_f32_e32 v74, v73, v72
	v_fma_f32 v75, -v55, v74, v73
	v_fmac_f32_e32 v74, v75, v72
	v_fma_f32 v55, -v55, v74, v73
	v_div_fmas_f32 v55, v55, v72, v74
	v_div_fixup_f32 v0, v55, v0, 1.0
	v_div_scale_f32 v55, s[8:9], v54, v54, v0
	v_rcp_f32_e32 v72, v55
	v_add_co_u32_e32 v46, vcc, s7, v46
	s_mov_b64 s[8:9], 0
	s_nop 0
	v_addc_co_u32_e32 v47, vcc, 0, v47, vcc
	v_fma_f32 v74, -v55, v72, 1.0
	v_div_scale_f32 v73, vcc, v0, v54, v0
	v_fmac_f32_e32 v72, v74, v72
	v_mul_f32_e32 v74, v73, v72
	v_fma_f32 v75, -v55, v74, v73
	v_fmac_f32_e32 v74, v75, v72
	v_fma_f32 v55, -v55, v74, v73
	v_div_fmas_f32 v55, v55, v72, v74
	v_div_fixup_f32 v0, v55, v54, v0
	s_waitcnt lgkmcnt(7)
	v_fma_f32 v2, v2, v0, v56
	v_fma_f32 v3, v3, v0, v57
	s_waitcnt lgkmcnt(5)
	v_fma_f32 v4, v4, v0, v60
	v_fma_f32 v5, v5, v0, v61
	s_waitcnt lgkmcnt(3)
	v_fma_f32 v6, v6, v0, v64
	v_fma_f32 v7, v7, v0, v65
	s_waitcnt lgkmcnt(1)
	v_fma_f32 v8, v8, v0, v68
	v_fma_f32 v9, v9, v0, v69
	v_fma_f32 v10, v10, v0, v40
	v_fma_f32 v11, v11, v0, v41
	v_fma_f32 v12, v12, v0, v44
	v_fma_f32 v13, v13, v0, v45
	v_fma_f32 v14, v14, v0, v42
	v_fma_f32 v15, v15, v0, v43
	v_fma_f32 v16, v16, v0, v48
	v_fma_f32 v17, v17, v0, v49
	v_fma_f32 v18, v18, v0, v58
	v_fma_f32 v19, v19, v0, v59
	v_fma_f32 v20, v20, v0, v62
	v_fma_f32 v21, v21, v0, v63
	v_fma_f32 v22, v22, v0, v66
	v_fma_f32 v23, v23, v0, v67
	s_waitcnt lgkmcnt(0)
	v_fma_f32 v24, v24, v0, v70
	v_fma_f32 v25, v25, v0, v71
	v_fma_f32 v26, v26, v0, v50
	v_fma_f32 v27, v27, v0, v51
	v_fma_f32 v28, v28, v0, v34
	v_fma_f32 v29, v29, v0, v35
	v_fma_f32 v30, v30, v0, v38
	v_fma_f32 v31, v31, v0, v39
	v_fma_f32 v32, v32, v0, v36
	v_fma_f32 v33, v33, v0, v37
	v_cvt_pk_bf16_f32 v2, v2, v3
	v_cvt_pk_bf16_f32 v3, v4, v5
	v_cvt_pk_bf16_f32 v4, v6, v7
	v_cvt_pk_bf16_f32 v5, v8, v9
	v_cvt_pk_bf16_f32 v6, v10, v11
	v_cvt_pk_bf16_f32 v7, v12, v13
	v_cvt_pk_bf16_f32 v8, v14, v15
	v_cvt_pk_bf16_f32 v9, v16, v17
	v_cvt_pk_bf16_f32 v10, v18, v19
	v_cvt_pk_bf16_f32 v11, v20, v21
	v_cvt_pk_bf16_f32 v12, v22, v23
	v_cvt_pk_bf16_f32 v13, v24, v25
	v_cvt_pk_bf16_f32 v14, v26, v27
	v_cvt_pk_bf16_f32 v15, v28, v29
	v_cvt_pk_bf16_f32 v16, v30, v31
	v_cvt_pk_bf16_f32 v17, v32, v33
	global_store_dwordx2 v[46:47], v[2:3], off offset:2048
	global_store_dwordx2 v[52:53], v[4:5], off offset:16
	global_store_dwordx2 v[52:53], v[6:7], off offset:32
	global_store_dwordx2 v[52:53], v[8:9], off offset:48
	global_store_dwordx2 v[52:53], v[10:11], off offset:64
	global_store_dwordx2 v[52:53], v[12:13], off offset:80
	global_store_dwordx2 v[52:53], v[14:15], off offset:96
	global_store_dwordx2 v[52:53], v[16:17], off offset:112

.LBB0_1252:
	s_or_b64 exec, exec, s[8:9]
	s_lshl_b32 s8, s7, 3
	s_or_b32 s8, s8, s56
	s_bfe_u32 s66, s8, 0x30001
	v_ashrrev_i32_e32 v86, 3, v87
	v_lshl_add_u32 v2, s66, 7, v86
	v_lshlrev_b32_e32 v0, 4, v84
	v_ashrrev_i32_e32 v3, 31, v2
	v_and_b32_e32 v131, 0x70, v0
	v_lshlrev_b64 v[10:11], 8, v[2:3]
	s_lshl_b32 s46, s6, 1
	v_or3_b32 v10, v131, s46, v10
	s_mov_b64 s[8:9], 0x4000
	v_lshl_add_u64 v[2:3], s[58:59], 0, v[10:11]
	v_lshl_add_u64 v[6:7], s[60:61], 0, v[10:11]
	v_lshl_add_u64 v[10:11], v[10:11], 0, s[8:9]
	v_lshl_add_u64 v[12:13], s[58:59], 0, v[10:11]
	v_lshl_add_u64 v[14:15], s[60:61], 0, v[10:11]
	global_load_dwordx4 v[2:5], v[2:3], off
	s_nop 0
	global_load_dwordx4 v[6:9], v[6:7], off
	s_nop 0
	global_load_dwordx4 v[10:13], v[12:13], off
	s_nop 0
	global_load_dwordx4 v[14:17], v[14:15], off
	s_lshl_b32 s7, s7, 4
	s_andn2_b32 s7, s7, 31
	s_sub_i32 s16, 0x7e0, s7
	v_and_b32_e32 v85, 31, v84
	v_or_b32_e32 v193, s16, v85
	v_ashrrev_i32_e32 v0, 5, v84
	v_lshl_add_u32 v132, s66, 11, v193
	v_mov_b64_e32 v[18:19], s[50:51]
	v_mad_i64_i32 v[82:83], s[8:9], v132, s84, v[18:19]
	s_lshl_b32 s72, s34, 1
	s_mov_b32 s73, s67
	v_lshlrev_b32_e32 v20, 3, v0
	v_lshl_add_u64 v[18:19], v[82:83], 0, s[72:73]
	v_ashrrev_i32_e32 v21, 31, v20
	v_lshl_add_u64 v[18:19], v[20:21], 1, v[18:19]
	global_load_dwordx4 v[98:101], v[18:19], off offset:2560
	global_load_dwordx4 v[102:105], v[18:19], off offset:2592
	global_load_dwordx4 v[106:109], v[18:19], off offset:2624
	global_load_dwordx4 v[110:113], v[18:19], off offset:2656
	v_lshrrev_b32_e32 v18, 2, v84
	v_lshlrev_b32_e32 v130, 2, v0
	v_mul_lo_u32 v194, v86, s86
	v_mul_lo_u32 v21, v86, 48
	v_and_or_b32 v22, v18, 3, v130
	v_add_u32_e32 v18, 0, v194
	v_lshlrev_b32_e32 v19, 1, v84
	v_add_u32_e32 v135, v18, v131
	v_add_u32_e32 v18, v18, v21
	s_movk_i32 s8, 0xffd0
	v_and_b32_e32 v20, 32, v19
	v_mad_u32_u24 v19, v85, s86, 0
	v_lshlrev_b32_e32 v195, 4, v0
	v_add_u32_e32 v134, v18, v131
	v_add_u32_e32 v42, v19, v195
	v_mad_u64_u32 v[18:19], s[8:9], v86, s8, v[134:135]
	v_add_u32_e32 v19, v18, v21
	s_waitcnt vmcnt(7)
	ds_write_b128 v135, v[2:5]
	s_waitcnt vmcnt(6)
	ds_write_b128 v134, v[6:9] offset:9216
	s_waitcnt vmcnt(5)
	ds_write_b128 v18, v[10:13] offset:21504
	s_waitcnt vmcnt(4)
	ds_write_b128 v19, v[14:17] offset:30720
	v_mov_b32_e32 v242, 0x1affc
	v_mov_b32_e32 v243, 0xf149f2ca
	ds_write_b32 v242, v243
	s_waitcnt lgkmcnt(0)
	s_barrier
	ds_read_b128 v[2:5], v42
	ds_read_b128 v[34:37], v42 offset:32
	ds_read_b128 v[6:9], v42 offset:4608
	ds_read_b128 v[38:41], v42 offset:4640
	ds_read_b128 v[44:47], v42 offset:64
	ds_read_b128 v[48:51], v42 offset:96
	ds_read_b128 v[52:55], v42 offset:4672
	ds_read_b128 v[56:59], v42 offset:4704
	v_lshlrev_b32_e32 v10, 3, v84
	v_and_b32_e32 v10, 24, v10
	v_mul_lo_u32 v11, v22, s85
	v_or3_b32 v196, v11, v20, v10
	s_waitcnt vmcnt(3) lgkmcnt(7)
	v_mfma_f32_32x32x16_bf16 v[18:33], v[2:5], v[98:101], 0
	s_waitcnt lgkmcnt(5)
	v_mfma_f32_32x32x16_bf16 v[2:17], v[6:9], v[98:101], 0
	s_waitcnt vmcnt(2)
	v_mfma_f32_32x32x16_bf16 v[18:33], v[34:37], v[102:105], v[18:33]
	s_waitcnt lgkmcnt(4)
	v_mfma_f32_32x32x16_bf16 v[2:17], v[38:41], v[102:105], v[2:17]
	s_waitcnt vmcnt(1) lgkmcnt(3)
	v_mfma_f32_32x32x16_bf16 v[18:33], v[44:47], v[106:109], v[18:33]
	v_add_u32_e32 v89, 0, v196
	ds_read_b64_tr_b16 v[34:35], v89 offset:9216
	ds_read_b64_tr_b16 v[36:37], v89 offset:10752
	ds_read_b64_tr_b16 v[40:41], v89 offset:10816
	ds_read_b64_tr_b16 v[38:39], v89 offset:9280
	v_subrev_u32_e32 v88, 31, v193
	v_lshlrev_b32_e32 v45, 6, v0
	v_sub_u32_e32 v46, v88, v45
	v_cmp_lt_i32_e32 vcc, -1, v46
	v_cmp_gt_i32_e64 s[8:9], 32, v0
	s_waitcnt lgkmcnt(5)
	v_mfma_f32_32x32x16_bf16 v[2:17], v[52:55], v[106:109], v[2:17]
	s_and_b64 s[10:11], s[8:9], vcc
	v_mov_b32_e32 v43, 0xf149f2ca
	v_mov_b32_e32 v44, 0xf149f2ca
	s_waitcnt vmcnt(0)
	s_add_i32 s100, s70, 0x1800
	s_mov_b32 s101, 0
	v_lshl_add_u64 v[244:245], v[82:83], 0, s[100:101]
	global_load_ushort v246, v[244:245], off
	global_load_ushort v247, v[244:245], off offset:2
	global_load_ushort v248, v[244:245], off offset:4
	v_mfma_f32_32x32x16_bf16 v[18:33], v[48:51], v[110:113], v[18:33]
	s_waitcnt lgkmcnt(4)
	v_mfma_f32_32x32x16_bf16 v[2:17], v[56:59], v[110:113], v[2:17]
	v_min_u32_e32 v210, 0x7f, v46
	v_lshl_add_u32 v210, v210, 2, s3
	v_cndmask_b32_e64 v210, v242, v210, s[10:11]
	ds_read_b32 v210, v210
	v_sub_u32_e32 v74, v193, v45
	v_add_u32_e32 v150, 0xfffffde1, v74
	v_cmp_lt_i32_e64 s[8:9], -1, v150
	v_cmp_gt_i32_e32 vcc, 24, v0
	s_and_b64 s[10:11], vcc, s[8:9]
	v_min_u32_e32 v211, 0x7f, v150
	v_lshl_add_u32 v211, v211, 2, s3
	v_cndmask_b32_e64 v211, v242, v211, s[10:11]
	ds_read_b32 v211, v211
	v_or_b32_e32 v151, 1, v130
	v_lshlrev_b32_e32 v152, 4, v151
	v_sub_u32_e32 v45, v88, v152
	v_cmp_lt_i32_e64 s[8:9], -1, v45
	v_cmp_gt_i32_e64 s[10:11], s82, v151
	s_and_b64 s[10:11], s[10:11], s[8:9]
	v_min_u32_e32 v212, 0x7f, v45
	v_lshl_add_u32 v212, v212, 2, s3
	v_cndmask_b32_e64 v212, v242, v212, s[10:11]
	ds_read_b32 v212, v212
	v_add_u32_e32 v153, 0xfffffdd1, v74
	v_cmp_lt_i32_e64 s[8:9], -1, v153
	s_and_b64 s[10:11], vcc, s[8:9]
	v_min_u32_e32 v213, 0x7f, v153
	v_lshl_add_u32 v213, v213, 2, s3
	v_cndmask_b32_e64 v213, v242, v213, s[10:11]
	ds_read_b32 v213, v213
	v_or_b32_e32 v154, 2, v130
	v_lshlrev_b32_e32 v155, 4, v154
	v_sub_u32_e32 v45, v88, v155
	v_cmp_lt_i32_e64 s[8:9], -1, v45
	v_cmp_gt_i32_e64 s[10:11], s82, v154
	s_and_b64 s[10:11], s[10:11], s[8:9]
	v_min_u32_e32 v214, 0x7f, v45
	v_lshl_add_u32 v214, v214, 2, s3
	v_cndmask_b32_e64 v214, v242, v214, s[10:11]
	ds_read_b32 v214, v214
	v_add_u32_e32 v156, 0xfffffdc1, v74
	v_cmp_lt_i32_e64 s[8:9], -1, v156
	s_and_b64 s[10:11], vcc, s[8:9]
	v_min_u32_e32 v215, 0x7f, v156
	v_lshl_add_u32 v215, v215, 2, s3
	v_cndmask_b32_e64 v215, v242, v215, s[10:11]
	ds_read_b32 v215, v215
	v_or_b32_e32 v157, 3, v130
	v_lshlrev_b32_e32 v158, 4, v157
	v_sub_u32_e32 v45, v88, v158
	v_cmp_lt_i32_e32 vcc, -1, v45
	v_cmp_gt_i32_e64 s[8:9], s82, v157
	s_and_b64 s[10:11], s[8:9], vcc
	v_min_u32_e32 v216, 0x7f, v45
	v_lshl_add_u32 v216, v216, 2, s3
	v_cndmask_b32_e64 v216, v242, v216, s[10:11]
	ds_read_b32 v216, v216
	v_add_u32_e32 v159, 0xfffffdb1, v74
	v_cmp_lt_i32_e32 vcc, -1, v159
	v_cmp_gt_i32_e64 s[8:9], 23, v0
	s_and_b64 s[10:11], s[8:9], vcc
	v_min_u32_e32 v217, 0x7f, v159
	v_lshl_add_u32 v217, v217, 2, s3
	v_cndmask_b32_e64 v217, v242, v217, s[10:11]
	ds_read_b32 v217, v217
	v_add_u32_e32 v45, 0xffffff61, v74
	v_cmp_lt_i32_e64 s[8:9], -1, v45
	v_cmp_gt_i32_e32 vcc, 30, v0
	s_and_b64 s[10:11], vcc, s[8:9]
	v_min_u32_e32 v218, 0x7f, v45
	v_lshl_add_u32 v218, v218, 2, s3
	v_cndmask_b32_e64 v218, v242, v218, s[10:11]
	ds_read_b32 v218, v218
	v_add_u32_e32 v160, 0xfffffd61, v74
	v_cmp_lt_i32_e64 s[10:11], -1, v160
	v_cmp_gt_i32_e64 s[8:9], 22, v0
	s_and_b64 s[12:13], s[8:9], s[10:11]
	v_min_u32_e32 v219, 0x7f, v160
	v_lshl_add_u32 v219, v219, 2, s3
	v_cndmask_b32_e64 v219, v242, v219, s[12:13]
	ds_read_b32 v219, v219
	v_add_u32_e32 v45, 0xffffff51, v74
	v_cmp_lt_i32_e64 s[10:11], -1, v45
	s_and_b64 s[12:13], vcc, s[10:11]
	v_min_u32_e32 v220, 0x7f, v45
	v_lshl_add_u32 v220, v220, 2, s3
	v_cndmask_b32_e64 v220, v242, v220, s[12:13]
	ds_read_b32 v220, v220
	v_add_u32_e32 v161, 0xfffffd51, v74
	v_cmp_lt_i32_e64 s[10:11], -1, v161
	s_and_b64 s[12:13], s[8:9], s[10:11]
	v_min_u32_e32 v221, 0x7f, v161
	v_lshl_add_u32 v221, v221, 2, s3
	v_cndmask_b32_e64 v221, v242, v221, s[12:13]
	ds_read_b32 v221, v221
	v_add_u32_e32 v45, 0xffffff41, v74
	v_cmp_lt_i32_e64 s[10:11], -1, v45
	s_and_b64 s[12:13], vcc, s[10:11]
	v_min_u32_e32 v222, 0x7f, v45
	v_lshl_add_u32 v222, v222, 2, s3
	v_cndmask_b32_e64 v222, v242, v222, s[12:13]
	ds_read_b32 v222, v222
	v_add_u32_e32 v162, 0xfffffd41, v74
	v_cmp_lt_i32_e32 vcc, -1, v162
	s_and_b64 s[10:11], s[8:9], vcc
	v_min_u32_e32 v223, 0x7f, v162
	v_lshl_add_u32 v223, v223, 2, s3
	v_cndmask_b32_e64 v223, v242, v223, s[10:11]
	ds_read_b32 v223, v223
	v_add_u32_e32 v45, 0xffffff31, v74
	v_cmp_lt_i32_e32 vcc, -1, v45
	v_cmp_gt_i32_e64 s[8:9], 29, v0
	s_and_b64 s[10:11], s[8:9], vcc
	v_min_u32_e32 v224, 0x7f, v45
	v_lshl_add_u32 v224, v224, 2, s3
	v_cndmask_b32_e64 v224, v242, v224, s[10:11]
	ds_read_b32 v224, v224
	v_add_u32_e32 v163, 0xfffffd31, v74
	v_cmp_lt_i32_e32 vcc, -1, v163
	v_cmp_gt_i32_e64 s[8:9], 21, v0
	s_and_b64 s[10:11], s[8:9], vcc
	v_min_u32_e32 v225, 0x7f, v163
	v_lshl_add_u32 v225, v225, 2, s3
	v_cndmask_b32_e64 v225, v242, v225, s[10:11]
	ds_read_b32 v225, v225
	v_add_u32_e32 v45, 0xfffffee1, v74
	v_cmp_lt_i32_e64 s[8:9], -1, v45
	v_cmp_gt_i32_e32 vcc, 28, v0
	s_and_b64 s[10:11], vcc, s[8:9]
	v_min_u32_e32 v226, 0x7f, v45
	v_lshl_add_u32 v226, v226, 2, s3
	v_cndmask_b32_e64 v226, v242, v226, s[10:11]
	ds_read_b32 v226, v226
	v_add_u32_e32 v164, 0xfffffce1, v74
	v_cmp_lt_i32_e64 s[10:11], -1, v164
	v_cmp_gt_i32_e64 s[8:9], 20, v0
	s_and_b64 s[12:13], s[8:9], s[10:11]
	v_min_u32_e32 v227, 0x7f, v164
	v_lshl_add_u32 v227, v227, 2, s3
	v_cndmask_b32_e64 v227, v242, v227, s[12:13]
	ds_read_b32 v227, v227
	v_add_u32_e32 v45, 0xfffffed1, v74
	v_cmp_lt_i32_e64 s[10:11], -1, v45
	s_and_b64 s[12:13], vcc, s[10:11]
	v_min_u32_e32 v228, 0x7f, v45
	v_lshl_add_u32 v228, v228, 2, s3
	v_cndmask_b32_e64 v228, v242, v228, s[12:13]
	ds_read_b32 v228, v228
	v_add_u32_e32 v165, 0xfffffcd1, v74
	v_cmp_lt_i32_e64 s[10:11], -1, v165
	s_and_b64 s[12:13], s[8:9], s[10:11]
	v_min_u32_e32 v229, 0x7f, v165
	v_lshl_add_u32 v229, v229, 2, s3
	v_cndmask_b32_e64 v229, v242, v229, s[12:13]
	ds_read_b32 v229, v229
	v_add_u32_e32 v45, 0xfffffec1, v74
	v_cmp_lt_i32_e64 s[10:11], -1, v45
	s_and_b64 s[12:13], vcc, s[10:11]
	v_min_u32_e32 v230, 0x7f, v45
	v_lshl_add_u32 v230, v230, 2, s3
	v_cndmask_b32_e64 v230, v242, v230, s[12:13]
	ds_read_b32 v230, v230
	v_add_u32_e32 v166, 0xfffffcc1, v74
	v_cmp_lt_i32_e32 vcc, -1, v166
	s_and_b64 s[10:11], s[8:9], vcc
	v_min_u32_e32 v231, 0x7f, v166
	v_lshl_add_u32 v231, v231, 2, s3
	v_cndmask_b32_e64 v231, v242, v231, s[10:11]
	ds_read_b32 v231, v231
	v_add_u32_e32 v45, 0xfffffeb1, v74
	v_cmp_lt_i32_e32 vcc, -1, v45
	v_cmp_gt_i32_e64 s[8:9], 27, v0
	s_and_b64 s[10:11], s[8:9], vcc
	v_min_u32_e32 v232, 0x7f, v45
	v_lshl_add_u32 v232, v232, 2, s3
	v_cndmask_b32_e64 v232, v242, v232, s[10:11]
	ds_read_b32 v232, v232
	v_add_u32_e32 v167, 0xfffffcb1, v74
	v_cmp_lt_i32_e32 vcc, -1, v167
	v_cmp_gt_i32_e64 s[8:9], 19, v0
	s_and_b64 s[10:11], s[8:9], vcc
	v_min_u32_e32 v233, 0x7f, v167
	v_lshl_add_u32 v233, v233, 2, s3
	v_cndmask_b32_e64 v233, v242, v233, s[10:11]
	ds_read_b32 v233, v233
	v_add_u32_e32 v45, 0xfffffe61, v74
	v_cmp_lt_i32_e64 s[8:9], -1, v45
	v_cmp_gt_i32_e32 vcc, 26, v0
	s_and_b64 s[10:11], vcc, s[8:9]
	v_min_u32_e32 v234, 0x7f, v45
	v_lshl_add_u32 v234, v234, 2, s3
	v_cndmask_b32_e64 v234, v242, v234, s[10:11]
	ds_read_b32 v234, v234
	v_add_u32_e32 v168, 0xfffffc61, v74
	v_cmp_lt_i32_e64 s[10:11], -1, v168
	v_cmp_gt_i32_e64 s[8:9], 18, v0
	s_and_b64 s[12:13], s[8:9], s[10:11]
	v_min_u32_e32 v235, 0x7f, v168
	v_lshl_add_u32 v235, v235, 2, s3
	v_cndmask_b32_e64 v235, v242, v235, s[12:13]
	ds_read_b32 v235, v235
	v_add_u32_e32 v45, 0xfffffe51, v74
	v_cmp_lt_i32_e64 s[10:11], -1, v45
	s_and_b64 s[12:13], vcc, s[10:11]
	v_min_u32_e32 v236, 0x7f, v45
	v_lshl_add_u32 v236, v236, 2, s3
	v_cndmask_b32_e64 v236, v242, v236, s[12:13]
	ds_read_b32 v236, v236
	v_add_u32_e32 v169, 0xfffffc51, v74
	v_cmp_lt_i32_e64 s[10:11], -1, v169
	s_and_b64 s[12:13], s[8:9], s[10:11]
	v_min_u32_e32 v237, 0x7f, v169
	v_lshl_add_u32 v237, v237, 2, s3
	v_cndmask_b32_e64 v237, v242, v237, s[12:13]
	ds_read_b32 v237, v237
	v_add_u32_e32 v45, 0xfffffe41, v74
	v_cmp_lt_i32_e64 s[10:11], -1, v45
	s_and_b64 s[12:13], vcc, s[10:11]
	v_min_u32_e32 v238, 0x7f, v45
	v_lshl_add_u32 v238, v238, 2, s3
	v_cndmask_b32_e64 v238, v242, v238, s[12:13]
	ds_read_b32 v238, v238
	v_add_u32_e32 v170, 0xfffffc41, v74
	v_cmp_lt_i32_e32 vcc, -1, v170
	s_and_b64 s[10:11], s[8:9], vcc
	v_min_u32_e32 v239, 0x7f, v170
	v_lshl_add_u32 v239, v239, 2, s3
	v_cndmask_b32_e64 v239, v242, v239, s[10:11]
	ds_read_b32 v239, v239
	v_add_u32_e32 v45, 0xfffffe31, v74
	v_cmp_lt_i32_e32 vcc, -1, v45
	v_cmp_gt_i32_e64 s[8:9], 25, v0
	s_and_b64 s[10:11], s[8:9], vcc
	v_min_u32_e32 v240, 0x7f, v45
	v_lshl_add_u32 v240, v240, 2, s3
	v_cndmask_b32_e64 v240, v242, v240, s[10:11]
	ds_read_b32 v240, v240
	v_add_u32_e32 v171, 0xfffffc31, v74
	v_cmp_lt_i32_e32 vcc, -1, v171
	v_cmp_gt_i32_e64 s[8:9], 17, v0
	s_and_b64 s[10:11], s[8:9], vcc
	v_min_u32_e32 v241, 0x7f, v171
	v_lshl_add_u32 v241, v241, 2, s3
	v_cndmask_b32_e64 v241, v242, v241, s[10:11]
	ds_read_b32 v241, v241
	s_waitcnt lgkmcnt(0)
	v_add_f32_e32 v44, v18, v210
	v_add_f32_e32 v43, v2, v211
	v_add_f32_e32 v18, v19, v212
	v_add_f32_e32 v2, v3, v213
	v_add_f32_e32 v19, v20, v214
	v_add_f32_e32 v3, v4, v215
	v_add_f32_e32 v20, v21, v216
	v_add_f32_e32 v4, v5, v217
	v_add_f32_e32 v21, v22, v218
	v_add_f32_e32 v5, v6, v219
	v_add_f32_e32 v22, v23, v220
	v_add_f32_e32 v6, v7, v221
	v_add_f32_e32 v23, v24, v222
	v_add_f32_e32 v7, v8, v223
	v_add_f32_e32 v24, v25, v224
	v_add_f32_e32 v8, v9, v225
	v_add_f32_e32 v25, v26, v226
	v_add_f32_e32 v9, v10, v227
	v_add_f32_e32 v26, v27, v228
	v_add_f32_e32 v10, v11, v229
	v_add_f32_e32 v27, v28, v230
	v_add_f32_e32 v11, v12, v231
	v_add_f32_e32 v28, v29, v232
	v_add_f32_e32 v12, v13, v233
	v_add_f32_e32 v29, v30, v234
	v_add_f32_e32 v13, v14, v235
	v_add_f32_e32 v30, v31, v236
	v_add_f32_e32 v14, v15, v237
	v_add_f32_e32 v31, v32, v238
	v_add_f32_e32 v15, v16, v239
	v_add_f32_e32 v32, v33, v240
	v_add_f32_e32 v16, v17, v241
	v_max3_f32 v17, v191, v44, v43
	v_lshlrev_b32_e32 v33, 7, v0
	v_max3_f32 v17, v17, v18, v2
	v_lshlrev_b32_e32 v45, 2, v85
	v_max3_f32 v17, v17, v19, v3
	s_movk_i32 s8, 0x80
	v_max3_f32 v17, v17, v20, v4
	v_bitop3_b32 v197, v33, s8, v45 bitop3:0x36
	v_max3_f32 v17, v17, v21, v5
	v_mov_b32_e32 v79, 0xf149f2ca
	v_max3_f32 v17, v17, v22, v6
	v_max3_f32 v17, v17, v23, v7
	v_max3_f32 v17, v17, v24, v8
	v_max3_f32 v17, v17, v25, v9
	v_max3_f32 v17, v17, v26, v10
	v_max3_f32 v17, v17, v27, v11
	v_max3_f32 v17, v17, v28, v12
	v_max3_f32 v17, v17, v29, v13
	v_max3_f32 v17, v17, v30, v14
	v_max3_f32 v17, v17, v31, v15
	v_max3_f32 v17, v17, v32, v16
	ds_bpermute_b32 v33, v197, v17
	v_max_f32_e32 v17, v17, v17
	s_waitcnt lgkmcnt(0)
	v_max_f32_e32 v33, v33, v33
	v_max_f32_e32 v17, v17, v33
	v_max_f32_e32 v75, 0xf149f2ca, v17
	v_sub_f32_e32 v5, v5, v75
	v_exp_f32_e32 v59, v5
	v_sub_f32_e32 v5, v22, v75
	v_exp_f32_e32 v22, v5
	v_sub_f32_e32 v5, v6, v75
	v_exp_f32_e32 v60, v5
	v_sub_f32_e32 v5, v23, v75
	v_exp_f32_e32 v23, v5
	v_sub_f32_e32 v5, v7, v75
	v_sub_f32_e32 v33, v44, v75
	v_sub_f32_e32 v43, v43, v75
	v_exp_f32_e32 v61, v5
	v_sub_f32_e32 v5, v24, v75
	v_exp_f32_e32 v33, v33
	v_exp_f32_e32 v43, v43
	v_sub_f32_e32 v18, v18, v75
	v_sub_f32_e32 v2, v2, v75
	v_sub_f32_e32 v3, v3, v75
	v_exp_f32_e32 v24, v5
	v_sub_f32_e32 v5, v8, v75
	v_exp_f32_e32 v18, v18
	v_exp_f32_e32 v56, v2
	v_sub_f32_e32 v19, v19, v75
	v_exp_f32_e32 v57, v3
	v_sub_f32_e32 v3, v20, v75
	v_exp_f32_e32 v62, v5
	v_sub_f32_e32 v5, v25, v75
	v_exp_f32_e32 v19, v19
	v_exp_f32_e32 v20, v3
	v_sub_f32_e32 v3, v4, v75
	v_exp_f32_e32 v63, v5
	v_sub_f32_e32 v5, v9, v75
	v_exp_f32_e32 v58, v3
	v_sub_f32_e32 v21, v21, v75
	v_exp_f32_e32 v64, v5
	v_sub_f32_e32 v5, v26, v75
	v_add_f32_e32 v44, v33, v43
	v_exp_f32_e32 v21, v21
	v_exp_f32_e32 v65, v5
	v_sub_f32_e32 v5, v10, v75
	v_add_f32_e32 v44, 0, v44
	v_add_f32_e32 v45, v18, v56
	v_exp_f32_e32 v66, v5
	v_sub_f32_e32 v5, v27, v75
	v_add_f32_e32 v3, v45, v44
	v_add_f32_e32 v4, v19, v57
	v_exp_f32_e32 v67, v5
	v_sub_f32_e32 v5, v11, v75
	v_add_f32_e32 v3, v4, v3
	v_add_f32_e32 v4, v20, v58
	v_exp_f32_e32 v68, v5
	v_sub_f32_e32 v5, v28, v75
	v_add_f32_e32 v3, v4, v3
	v_add_f32_e32 v4, v21, v59
	v_exp_f32_e32 v69, v5
	v_sub_f32_e32 v5, v12, v75
	v_add_f32_e32 v3, v4, v3
	v_add_f32_e32 v4, v22, v60
	v_exp_f32_e32 v70, v5
	v_sub_f32_e32 v5, v29, v75
	v_add_f32_e32 v3, v4, v3
	v_add_f32_e32 v4, v23, v61
	v_exp_f32_e32 v71, v5
	v_sub_f32_e32 v5, v13, v75
	v_add_f32_e32 v3, v4, v3
	v_add_f32_e32 v4, v24, v62
	v_exp_f32_e32 v72, v5
	v_sub_f32_e32 v5, v30, v75
	v_add_f32_e32 v3, v4, v3
	v_add_f32_e32 v4, v63, v64
	v_exp_f32_e32 v73, v5
	v_sub_f32_e32 v5, v14, v75
	v_add_f32_e32 v3, v4, v3
	v_add_f32_e32 v4, v65, v66
	v_exp_f32_e32 v80, v5
	v_add_f32_e32 v3, v4, v3
	v_add_f32_e32 v4, v67, v68
	v_add_f32_e32 v3, v4, v3
	v_add_f32_e32 v4, v69, v70
	v_add_f32_e32 v3, v4, v3
	v_add_f32_e32 v4, v71, v72
	v_add_f32_e32 v3, v4, v3
	v_add_f32_e32 v4, v73, v80
	v_add_f32_e32 v3, v4, v3
	v_sub_f32_e32 v4, v31, v75
	v_exp_f32_e32 v81, v4
	v_sub_f32_e32 v4, v15, v75
	v_exp_f32_e32 v90, v4
	v_sub_f32_e32 v4, v32, v75
	v_exp_f32_e32 v91, v4
	v_sub_f32_e32 v4, v16, v75
	v_exp_f32_e32 v92, v4
	v_sub_f32_e32 v2, 0xf149f2ca, v75
	v_add_f32_e32 v4, v81, v90
	v_add_f32_e32 v3, v4, v3
	v_exp_f32_e32 v2, v2
	v_add_f32_e32 v4, v91, v92
	v_add_f32_e32 v76, v4, v3
	ds_bpermute_b32 v77, v197, v76
	v_cmp_gt_f32_e32 vcc, v17, v79
	s_cmp_lg_u64 vcc, 0
	v_mul_f32_e32 v78, 0, v2
	s_cselect_b64 vcc, -1, 0
	v_cndmask_b32_e32 v2, 0, v78, vcc
	v_mov_b32_e32 v3, v2
	v_mov_b32_e32 v4, v2
	v_mov_b32_e32 v5, v2
	v_mov_b32_e32 v6, v2
	v_mov_b32_e32 v7, v2
	v_mov_b32_e32 v8, v2
	v_mov_b32_e32 v9, v2
	v_mov_b32_e32 v10, v2
	v_mov_b32_e32 v11, v2
	v_mov_b32_e32 v12, v2
	v_mov_b32_e32 v13, v2
	v_mov_b32_e32 v14, v2
	v_mov_b32_e32 v15, v2
	v_mov_b32_e32 v16, v2
	v_mov_b32_e32 v17, v2
	ds_read_b64_tr_b16 v[44:45], v89 offset:12288
	ds_read_b64_tr_b16 v[46:47], v89 offset:13824
	ds_read_b64_tr_b16 v[50:51], v89 offset:13888
	ds_read_b64_tr_b16 v[48:49], v89 offset:12352
	v_cvt_pk_bf16_f32 v52, v33, v18
	v_cvt_pk_bf16_f32 v53, v19, v20
	v_cvt_pk_bf16_f32 v54, v21, v22
	v_cvt_pk_bf16_f32 v55, v23, v24
	s_nop 1
	v_mfma_f32_32x32x16_bf16 v[18:33], v[34:37], v[52:55], v[2:17]
	v_mfma_f32_32x32x16_bf16 v[2:17], v[38:41], v[52:55], v[2:17]
	ds_read_b64_tr_b16 v[34:35], v89 offset:15360
	ds_read_b64_tr_b16 v[36:37], v89 offset:16896
	ds_read_b64_tr_b16 v[40:41], v89 offset:16960
	ds_read_b64_tr_b16 v[38:39], v89 offset:15424
	v_cvt_pk_bf16_f32 v52, v63, v65
	v_cvt_pk_bf16_f32 v53, v67, v69
	v_cvt_pk_bf16_f32 v54, v71, v73
	v_cvt_pk_bf16_f32 v55, v81, v91
	s_waitcnt lgkmcnt(6)
	s_nop 0
	v_mfma_f32_32x32x16_bf16 v[18:33], v[44:47], v[52:55], v[18:33]
	s_waitcnt lgkmcnt(4)
	v_mfma_f32_32x32x16_bf16 v[2:17], v[48:51], v[52:55], v[2:17]
	ds_read_b64_tr_b16 v[44:45], v89 offset:18432
	ds_read_b64_tr_b16 v[46:47], v89 offset:19968
	ds_read_b64_tr_b16 v[50:51], v89 offset:20032
	ds_read_b64_tr_b16 v[48:49], v89 offset:18496
	v_cvt_pk_bf16_f32 v52, v43, v56
	v_cvt_pk_bf16_f32 v53, v57, v58
	v_cvt_pk_bf16_f32 v54, v59, v60
	v_cvt_pk_bf16_f32 v55, v61, v62
	s_waitcnt lgkmcnt(6)
	s_nop 0
	v_mfma_f32_32x32x16_bf16 v[18:33], v[34:37], v[52:55], v[18:33]
	s_waitcnt lgkmcnt(4)
	v_mfma_f32_32x32x16_bf16 v[2:17], v[38:41], v[52:55], v[2:17]
	v_cvt_pk_bf16_f32 v34, v64, v66
	v_cvt_pk_bf16_f32 v35, v68, v70
	v_cvt_pk_bf16_f32 v36, v72, v80
	v_cvt_pk_bf16_f32 v37, v90, v92
	s_waitcnt lgkmcnt(2)
	s_nop 0
	v_mfma_f32_32x32x16_bf16 v[18:33], v[44:47], v[34:37], v[18:33]
	s_waitcnt lgkmcnt(0)
	v_mfma_f32_32x32x16_bf16 v[2:17], v[48:51], v[34:37], v[2:17]
	ds_read_b128 v[34:37], v42 offset:21504
	ds_read_b128 v[66:69], v42 offset:21536
	ds_read_b128 v[38:41], v42 offset:26112
	ds_read_b128 v[70:73], v42 offset:26144
	ds_read_b128 v[90:93], v42 offset:21568
	ds_read_b128 v[94:97], v42 offset:21600
	ds_read_b128 v[114:117], v42 offset:26176
	ds_read_b128 v[118:121], v42 offset:26208
	s_waitcnt lgkmcnt(7)
	v_mfma_f32_32x32x16_bf16 v[50:65], v[34:37], v[98:101], 0
	s_waitcnt lgkmcnt(5)
	v_mfma_f32_32x32x16_bf16 v[34:49], v[38:41], v[98:101], 0
	v_mfma_f32_32x32x16_bf16 v[50:65], v[66:69], v[102:105], v[50:65]
	s_waitcnt lgkmcnt(4)
	v_mfma_f32_32x32x16_bf16 v[34:49], v[70:73], v[102:105], v[34:49]
	s_waitcnt lgkmcnt(3)
	v_mfma_f32_32x32x16_bf16 v[50:65], v[90:93], v[106:109], v[50:65]
	ds_read_b64_tr_b16 v[66:67], v89 offset:30720
	ds_read_b64_tr_b16 v[68:69], v89 offset:32256
	ds_read_b64_tr_b16 v[72:73], v89 offset:32320
	ds_read_b64_tr_b16 v[70:71], v89 offset:30784
	v_add_u32_e32 v81, 0xfffffbe1, v74
	v_cmp_lt_i32_e64 s[8:9], -1, v81
	v_cmp_gt_i32_e32 vcc, 16, v0
	s_and_b64 s[10:11], vcc, s[8:9]
	v_mov_b32_e32 v80, 0xf149f2ca
	s_waitcnt lgkmcnt(5)
	v_mfma_f32_32x32x16_bf16 v[34:49], v[114:117], v[106:109], v[34:49]
	v_mfma_f32_32x32x16_bf16 v[50:65], v[94:97], v[110:113], v[50:65]
	s_waitcnt lgkmcnt(4)
	v_mfma_f32_32x32x16_bf16 v[34:49], v[118:121], v[110:113], v[34:49]
	v_min_u32_e32 v210, 0x7f, v81
	v_lshl_add_u32 v210, v210, 2, s3
	v_cndmask_b32_e64 v210, v242, v210, s[10:11]
	ds_read_b32 v210, v210
	s_nop 6
	v_add_u32_e32 v150, 0xfffff9e1, v74
	v_cmp_lt_i32_e64 s[10:11], -1, v150
	v_cmp_gt_i32_e64 s[8:9], 8, v0
	s_and_b64 s[12:13], s[8:9], s[10:11]
	v_min_u32_e32 v211, 0x7f, v150
	v_lshl_add_u32 v211, v211, 2, s3
	v_cndmask_b32_e64 v211, v242, v211, s[12:13]
	ds_read_b32 v211, v211
	v_add_u32_e32 v81, 0xfffffbd1, v74
	v_cmp_lt_i32_e64 s[10:11], -1, v81
	s_and_b64 s[12:13], vcc, s[10:11]
	v_min_u32_e32 v212, 0x7f, v81
	v_lshl_add_u32 v212, v212, 2, s3
	v_cndmask_b32_e64 v212, v242, v212, s[12:13]
	ds_read_b32 v212, v212
	v_add_u32_e32 v151, 0xfffff9d1, v74
	v_cmp_lt_i32_e64 s[10:11], -1, v151
	s_and_b64 s[12:13], s[8:9], s[10:11]
	v_min_u32_e32 v213, 0x7f, v151
	v_lshl_add_u32 v213, v213, 2, s3
	v_cndmask_b32_e64 v213, v242, v213, s[12:13]
	ds_read_b32 v213, v213
	v_add_u32_e32 v81, 0xfffffbc1, v74
	v_cmp_lt_i32_e64 s[10:11], -1, v81
	s_and_b64 s[12:13], vcc, s[10:11]
	v_min_u32_e32 v214, 0x7f, v81
	v_lshl_add_u32 v214, v214, 2, s3
	v_cndmask_b32_e64 v214, v242, v214, s[12:13]
	ds_read_b32 v214, v214
	v_add_u32_e32 v152, 0xfffff9c1, v74
	v_cmp_lt_i32_e32 vcc, -1, v152
	s_and_b64 s[10:11], s[8:9], vcc
	v_min_u32_e32 v215, 0x7f, v152
	v_lshl_add_u32 v215, v215, 2, s3
	v_cndmask_b32_e64 v215, v242, v215, s[10:11]
	ds_read_b32 v215, v215
	v_add_u32_e32 v81, 0xfffffbb1, v74
	v_cmp_lt_i32_e32 vcc, -1, v81
	v_cmp_gt_i32_e64 s[8:9], 15, v0
	s_and_b64 s[10:11], s[8:9], vcc
	v_min_u32_e32 v216, 0x7f, v81
	v_lshl_add_u32 v216, v216, 2, s3
	v_cndmask_b32_e64 v216, v242, v216, s[10:11]
	ds_read_b32 v216, v216
	v_add_u32_e32 v153, 0xfffff9b1, v74
	v_cmp_lt_i32_e32 vcc, -1, v153
	v_cmp_gt_i32_e64 s[8:9], 7, v0
	s_and_b64 s[10:11], s[8:9], vcc
	v_min_u32_e32 v217, 0x7f, v153
	v_lshl_add_u32 v217, v217, 2, s3
	v_cndmask_b32_e64 v217, v242, v217, s[10:11]
	ds_read_b32 v217, v217
	v_add_u32_e32 v81, 0xfffffb61, v74
	v_cmp_lt_i32_e64 s[8:9], -1, v81
	v_cmp_gt_i32_e32 vcc, 14, v0
	s_and_b64 s[10:11], vcc, s[8:9]
	v_min_u32_e32 v218, 0x7f, v81
	v_lshl_add_u32 v218, v218, 2, s3
	v_cndmask_b32_e64 v218, v242, v218, s[10:11]
	ds_read_b32 v218, v218
	v_add_u32_e32 v154, 0xfffff961, v74
	v_cmp_lt_i32_e64 s[10:11], -1, v154
	v_cmp_gt_i32_e64 s[8:9], 6, v0
	s_and_b64 s[12:13], s[8:9], s[10:11]
	v_min_u32_e32 v219, 0x7f, v154
	v_lshl_add_u32 v219, v219, 2, s3
	v_cndmask_b32_e64 v219, v242, v219, s[12:13]
	ds_read_b32 v219, v219
	v_add_u32_e32 v81, 0xfffffb51, v74
	v_cmp_lt_i32_e64 s[10:11], -1, v81
	s_and_b64 s[12:13], vcc, s[10:11]
	v_min_u32_e32 v220, 0x7f, v81
	v_lshl_add_u32 v220, v220, 2, s3
	v_cndmask_b32_e64 v220, v242, v220, s[12:13]
	ds_read_b32 v220, v220
	v_add_u32_e32 v155, 0xfffff951, v74
	v_cmp_lt_i32_e64 s[10:11], -1, v155
	s_and_b64 s[12:13], s[8:9], s[10:11]
	v_min_u32_e32 v221, 0x7f, v155
	v_lshl_add_u32 v221, v221, 2, s3
	v_cndmask_b32_e64 v221, v242, v221, s[12:13]
	ds_read_b32 v221, v221
	v_add_u32_e32 v81, 0xfffffb41, v74
	v_cmp_lt_i32_e64 s[10:11], -1, v81
	s_and_b64 s[12:13], vcc, s[10:11]
	v_min_u32_e32 v222, 0x7f, v81
	v_lshl_add_u32 v222, v222, 2, s3
	v_cndmask_b32_e64 v222, v242, v222, s[12:13]
	ds_read_b32 v222, v222
	v_add_u32_e32 v156, 0xfffff941, v74
	v_cmp_lt_i32_e32 vcc, -1, v156
	s_and_b64 s[10:11], s[8:9], vcc
	v_min_u32_e32 v223, 0x7f, v156
	v_lshl_add_u32 v223, v223, 2, s3
	v_cndmask_b32_e64 v223, v242, v223, s[10:11]
	ds_read_b32 v223, v223
	v_add_u32_e32 v81, 0xfffffb31, v74
	v_cmp_lt_i32_e32 vcc, -1, v81
	v_cmp_gt_i32_e64 s[8:9], 13, v0
	s_and_b64 s[10:11], s[8:9], vcc
	v_min_u32_e32 v224, 0x7f, v81
	v_lshl_add_u32 v224, v224, 2, s3
	v_cndmask_b32_e64 v224, v242, v224, s[10:11]
	ds_read_b32 v224, v224
	v_add_u32_e32 v157, 0xfffff931, v74
	v_cmp_lt_i32_e32 vcc, -1, v157
	v_cmp_gt_i32_e64 s[8:9], 5, v0
	s_and_b64 s[10:11], s[8:9], vcc
	v_min_u32_e32 v225, 0x7f, v157
	v_lshl_add_u32 v225, v225, 2, s3
	v_cndmask_b32_e64 v225, v242, v225, s[10:11]
	ds_read_b32 v225, v225
	v_add_u32_e32 v81, 0xfffffae1, v74
	v_cmp_lt_i32_e64 s[8:9], -1, v81
	v_cmp_gt_i32_e32 vcc, 12, v0
	s_and_b64 s[10:11], vcc, s[8:9]
	v_min_u32_e32 v226, 0x7f, v81
	v_lshl_add_u32 v226, v226, 2, s3
	v_cndmask_b32_e64 v226, v242, v226, s[10:11]
	ds_read_b32 v226, v226
	v_add_u32_e32 v158, 0xfffff8e1, v74
	v_cmp_lt_i32_e64 s[10:11], -1, v158
	v_cmp_gt_i32_e64 s[8:9], 4, v0
	s_and_b64 s[12:13], s[8:9], s[10:11]
	v_min_u32_e32 v227, 0x7f, v158
	v_lshl_add_u32 v227, v227, 2, s3
	v_cndmask_b32_e64 v227, v242, v227, s[12:13]
	ds_read_b32 v227, v227
	v_add_u32_e32 v81, 0xfffffad1, v74
	v_cmp_lt_i32_e64 s[10:11], -1, v81
	s_and_b64 s[12:13], vcc, s[10:11]
	v_min_u32_e32 v228, 0x7f, v81
	v_lshl_add_u32 v228, v228, 2, s3
	v_cndmask_b32_e64 v228, v242, v228, s[12:13]
	ds_read_b32 v228, v228
	v_add_u32_e32 v159, 0xfffff8d1, v74
	v_cmp_lt_i32_e64 s[10:11], -1, v159
	s_and_b64 s[12:13], s[8:9], s[10:11]
	v_min_u32_e32 v229, 0x7f, v159
	v_lshl_add_u32 v229, v229, 2, s3
	v_cndmask_b32_e64 v229, v242, v229, s[12:13]
	ds_read_b32 v229, v229
	v_add_u32_e32 v81, 0xfffffac1, v74
	v_cmp_lt_i32_e64 s[10:11], -1, v81
	s_and_b64 s[12:13], vcc, s[10:11]
	v_min_u32_e32 v230, 0x7f, v81
	v_lshl_add_u32 v230, v230, 2, s3
	v_cndmask_b32_e64 v230, v242, v230, s[12:13]
	ds_read_b32 v230, v230
	v_add_u32_e32 v160, 0xfffff8c1, v74
	v_cmp_lt_i32_e32 vcc, -1, v160
	s_and_b64 s[10:11], s[8:9], vcc
	v_min_u32_e32 v231, 0x7f, v160
	v_lshl_add_u32 v231, v231, 2, s3
	v_cndmask_b32_e64 v231, v242, v231, s[10:11]
	ds_read_b32 v231, v231
	v_add_u32_e32 v81, 0xfffffab1, v74
	v_cmp_lt_i32_e32 vcc, -1, v81
	v_cmp_gt_i32_e64 s[8:9], 11, v0
	s_and_b64 s[10:11], s[8:9], vcc
	v_min_u32_e32 v232, 0x7f, v81
	v_lshl_add_u32 v232, v232, 2, s3
	v_cndmask_b32_e64 v232, v242, v232, s[10:11]
	ds_read_b32 v232, v232
	v_add_u32_e32 v161, 0xfffff8b1, v74
	v_cmp_lt_i32_e32 vcc, -1, v161
	v_cmp_gt_i32_e64 s[8:9], 3, v0
	s_and_b64 s[10:11], s[8:9], vcc
	v_min_u32_e32 v233, 0x7f, v161
	v_lshl_add_u32 v233, v233, 2, s3
	v_cndmask_b32_e64 v233, v242, v233, s[10:11]
	ds_read_b32 v233, v233
	v_add_u32_e32 v81, 0xfffffa61, v74
	v_cmp_lt_i32_e64 s[8:9], -1, v81
	v_cmp_gt_i32_e32 vcc, 10, v0
	s_and_b64 s[10:11], vcc, s[8:9]
	v_min_u32_e32 v234, 0x7f, v81
	v_lshl_add_u32 v234, v234, 2, s3
	v_cndmask_b32_e64 v234, v242, v234, s[10:11]
	ds_read_b32 v234, v234
	v_add_u32_e32 v162, 0xfffff861, v74
	v_cmp_lt_i32_e64 s[10:11], -1, v162
	v_cmp_gt_i32_e64 s[8:9], 2, v0
	s_and_b64 s[12:13], s[8:9], s[10:11]
	v_min_u32_e32 v235, 0x7f, v162
	v_lshl_add_u32 v235, v235, 2, s3
	v_cndmask_b32_e64 v235, v242, v235, s[12:13]
	ds_read_b32 v235, v235
	v_add_u32_e32 v81, 0xfffffa51, v74
	v_cmp_lt_i32_e64 s[10:11], -1, v81
	s_and_b64 s[12:13], vcc, s[10:11]
	v_min_u32_e32 v236, 0x7f, v81
	v_lshl_add_u32 v236, v236, 2, s3
	v_cndmask_b32_e64 v236, v242, v236, s[12:13]
	ds_read_b32 v236, v236
	v_add_u32_e32 v163, 0xfffff851, v74
	v_cmp_lt_i32_e64 s[10:11], -1, v163
	s_and_b64 s[12:13], s[8:9], s[10:11]
	v_min_u32_e32 v237, 0x7f, v163
	v_lshl_add_u32 v237, v237, 2, s3
	v_cndmask_b32_e64 v237, v242, v237, s[12:13]
	ds_read_b32 v237, v237
	v_add_u32_e32 v81, 0xfffffa41, v74
	v_cmp_lt_i32_e64 s[10:11], -1, v81
	s_and_b64 s[12:13], vcc, s[10:11]
	v_min_u32_e32 v238, 0x7f, v81
	v_lshl_add_u32 v238, v238, 2, s3
	v_cndmask_b32_e64 v238, v242, v238, s[12:13]
	ds_read_b32 v238, v238
	v_add_u32_e32 v164, 0xfffff841, v74
	v_cmp_lt_i32_e32 vcc, -1, v164
	s_and_b64 s[10:11], s[8:9], vcc
	v_min_u32_e32 v239, 0x7f, v164
	v_lshl_add_u32 v239, v239, 2, s3
	v_cndmask_b32_e64 v239, v242, v239, s[10:11]
	ds_read_b32 v239, v239
	v_add_u32_e32 v81, 0xfffffa31, v74
	v_cmp_lt_i32_e32 vcc, -1, v81
	v_cmp_gt_i32_e64 s[8:9], 9, v0
	s_and_b64 s[10:11], s[8:9], vcc
	v_min_u32_e32 v240, 0x7f, v81
	v_lshl_add_u32 v240, v240, 2, s3
	v_cndmask_b32_e64 v240, v242, v240, s[10:11]
	ds_read_b32 v240, v240
	v_add_u32_e32 v165, 0xfffff831, v74
	v_cmp_lt_i32_e32 vcc, -1, v165
	v_cmp_gt_i32_e64 s[8:9], 1, v0
	s_and_b64 s[10:11], s[8:9], vcc
	v_min_u32_e32 v241, 0x7f, v165
	v_lshl_add_u32 v241, v241, 2, s3
	v_cndmask_b32_e64 v241, v242, v241, s[10:11]
	ds_read_b32 v241, v241
	s_waitcnt lgkmcnt(0)
	v_add_f32_e32 v80, v50, v210
	v_add_f32_e32 v79, v34, v211
	v_add_f32_e32 v50, v51, v212
	v_add_f32_e32 v34, v35, v213
	v_add_f32_e32 v51, v52, v214
	v_add_f32_e32 v35, v36, v215
	v_add_f32_e32 v52, v53, v216
	v_add_f32_e32 v36, v37, v217
	v_add_f32_e32 v53, v54, v218
	v_add_f32_e32 v37, v38, v219
	v_add_f32_e32 v54, v55, v220
	v_add_f32_e32 v38, v39, v221
	v_add_f32_e32 v55, v56, v222
	v_add_f32_e32 v39, v40, v223
	v_add_f32_e32 v56, v57, v224
	v_add_f32_e32 v40, v41, v225
	v_add_f32_e32 v57, v58, v226
	v_add_f32_e32 v41, v42, v227
	v_add_f32_e32 v58, v59, v228
	v_add_f32_e32 v42, v43, v229
	v_add_f32_e32 v59, v60, v230
	v_add_f32_e32 v43, v44, v231
	v_add_f32_e32 v60, v61, v232
	v_add_f32_e32 v44, v45, v233
	v_add_f32_e32 v61, v62, v234
	v_add_f32_e32 v45, v46, v235
	v_add_f32_e32 v62, v63, v236
	v_add_f32_e32 v46, v47, v237
	v_add_f32_e32 v63, v64, v238
	v_add_f32_e32 v47, v48, v239
	v_add_f32_e32 v64, v65, v240
	v_add_f32_e32 v48, v49, v241
	v_max3_f32 v0, v191, v80, v79
	v_max_f32_e32 v65, v75, v75
	v_max3_f32 v0, v0, v50, v34
	v_max3_f32 v0, v0, v51, v35
	v_max3_f32 v0, v0, v52, v36
	v_max3_f32 v0, v0, v53, v37
	v_max3_f32 v0, v0, v54, v38
	v_max3_f32 v0, v0, v55, v39
	v_max3_f32 v0, v0, v56, v40
	v_max3_f32 v0, v0, v57, v41
	v_max3_f32 v0, v0, v58, v42
	v_max3_f32 v0, v0, v59, v43
	v_max3_f32 v0, v0, v60, v44
	v_max3_f32 v0, v0, v61, v45
	v_max3_f32 v0, v0, v62, v46
	v_max3_f32 v0, v0, v63, v47
	v_max3_f32 v0, v0, v64, v48
	ds_bpermute_b32 v49, v197, v0
	v_max_f32_e32 v0, v0, v0
	s_waitcnt lgkmcnt(0)
	v_max_f32_e32 v49, v49, v49
	v_max_f32_e32 v49, v0, v49
	v_max_f32_e32 v118, v65, v49
	v_sub_f32_e32 v35, v35, v118
	v_exp_f32_e32 v92, v35
	v_sub_f32_e32 v35, v52, v118
	v_exp_f32_e32 v125, v35
	v_sub_f32_e32 v35, v36, v118
	v_sub_f32_e32 v36, v53, v118
	v_exp_f32_e32 v136, v36
	v_sub_f32_e32 v36, v37, v118
	v_exp_f32_e32 v94, v36
	v_sub_f32_e32 v36, v54, v118
	v_exp_f32_e32 v138, v36
	v_sub_f32_e32 v36, v38, v118
	v_exp_f32_e32 v95, v36
	v_sub_f32_e32 v36, v55, v118
	v_exp_f32_e32 v141, v36
	v_sub_f32_e32 v36, v39, v118
	v_exp_f32_e32 v96, v36
	v_sub_f32_e32 v36, v56, v118
	v_sub_f32_e32 v0, v80, v118
	v_exp_f32_e32 v142, v36
	v_sub_f32_e32 v36, v40, v118
	v_sub_f32_e32 v65, v79, v118
	v_exp_f32_e32 v116, v0
	v_sub_f32_e32 v0, v50, v118
	v_exp_f32_e32 v97, v36
	v_sub_f32_e32 v36, v57, v118
	v_exp_f32_e32 v90, v65
	v_exp_f32_e32 v119, v0
	v_sub_f32_e32 v0, v34, v118
	v_exp_f32_e32 v120, v36
	v_sub_f32_e32 v36, v41, v118
	v_exp_f32_e32 v91, v0
	v_sub_f32_e32 v51, v51, v118
	v_exp_f32_e32 v114, v36
	v_sub_f32_e32 v36, v58, v118
	v_exp_f32_e32 v123, v51
	v_exp_f32_e32 v122, v36
	v_sub_f32_e32 v36, v42, v118
	v_exp_f32_e32 v93, v35
	v_exp_f32_e32 v115, v36
	v_sub_f32_e32 v36, v59, v118
	v_add_f32_e32 v34, v116, v90
	v_exp_f32_e32 v126, v36
	v_sub_f32_e32 v36, v43, v118
	v_add_f32_e32 v34, 0, v34
	v_add_f32_e32 v50, v119, v91
	v_exp_f32_e32 v117, v36
	v_sub_f32_e32 v36, v60, v118
	v_add_f32_e32 v34, v50, v34
	v_add_f32_e32 v35, v123, v92
	v_exp_f32_e32 v128, v36
	v_sub_f32_e32 v36, v44, v118
	v_add_f32_e32 v34, v35, v34
	v_add_f32_e32 v35, v125, v93
	v_exp_f32_e32 v121, v36
	v_sub_f32_e32 v36, v61, v118
	v_add_f32_e32 v34, v35, v34
	v_add_f32_e32 v35, v136, v94
	v_exp_f32_e32 v139, v36
	v_sub_f32_e32 v36, v45, v118
	v_add_f32_e32 v34, v35, v34
	v_add_f32_e32 v35, v138, v95
	v_exp_f32_e32 v124, v36
	v_sub_f32_e32 v36, v62, v118
	v_add_f32_e32 v34, v35, v34
	v_add_f32_e32 v35, v141, v96
	v_exp_f32_e32 v140, v36
	v_sub_f32_e32 v36, v46, v118
	v_add_f32_e32 v34, v35, v34
	v_add_f32_e32 v35, v142, v97
	v_exp_f32_e32 v127, v36
	v_sub_f32_e32 v36, v63, v118
	v_add_f32_e32 v34, v35, v34
	v_add_f32_e32 v35, v120, v114
	v_exp_f32_e32 v143, v36
	v_sub_f32_e32 v36, v47, v118
	v_add_f32_e32 v34, v35, v34
	v_add_f32_e32 v35, v122, v115
	v_exp_f32_e32 v129, v36
	v_sub_f32_e32 v36, v64, v118
	v_add_f32_e32 v34, v35, v34
	v_add_f32_e32 v35, v126, v117
	v_exp_f32_e32 v144, v36
	v_sub_f32_e32 v36, v48, v118
	v_add_f32_e32 v34, v35, v34
	v_add_f32_e32 v35, v128, v121
	v_exp_f32_e32 v137, v36
	v_add_f32_e32 v34, v35, v34
	v_add_f32_e32 v35, v139, v124
	v_add_f32_e32 v34, v35, v34
	v_add_f32_e32 v35, v140, v127
	v_add_f32_e32 v34, v35, v34
	v_add_f32_e32 v35, v143, v129
	v_add_f32_e32 v34, v35, v34
	v_add_f32_e32 v35, v144, v137
	v_add_f32_e32 v34, v35, v34
	v_sub_f32_e32 v0, v75, v118
	ds_bpermute_b32 v35, v197, v34
	v_exp_f32_e32 v0, v0
	v_cmp_gt_f32_e32 vcc, v49, v75
	s_cbranch_vccz .LBB0_1382
	v_mul_f32_e32 v32, v32, v0
	v_mul_f32_e32 v33, v33, v0
	v_mul_f32_e32 v30, v30, v0
	v_mul_f32_e32 v31, v31, v0
	v_mul_f32_e32 v28, v28, v0
	v_mul_f32_e32 v29, v29, v0
	v_mul_f32_e32 v26, v26, v0
	v_mul_f32_e32 v27, v27, v0
	v_mul_f32_e32 v24, v24, v0
	v_mul_f32_e32 v25, v25, v0
	v_mul_f32_e32 v22, v22, v0
	v_mul_f32_e32 v23, v23, v0
	v_mul_f32_e32 v20, v20, v0
	v_mul_f32_e32 v21, v21, v0
	v_mul_f32_e32 v18, v18, v0
	v_mul_f32_e32 v19, v19, v0
	v_mul_f32_e32 v16, v16, v0
	v_mul_f32_e32 v17, v17, v0
	v_mul_f32_e32 v14, v14, v0
	v_mul_f32_e32 v15, v15, v0
	v_mul_f32_e32 v12, v12, v0
	v_mul_f32_e32 v13, v13, v0
	v_mul_f32_e32 v10, v10, v0
	v_mul_f32_e32 v11, v11, v0
	v_mul_f32_e32 v8, v8, v0
	v_mul_f32_e32 v9, v9, v0
	v_mul_f32_e32 v6, v6, v0
	v_mul_f32_e32 v7, v7, v0
	v_mul_f32_e32 v4, v4, v0
	v_mul_f32_e32 v5, v5, v0
	v_mul_f32_e32 v2, v2, v0
	v_mul_f32_e32 v3, v3, v0

.LBB0_1416:
	v_cvt_pk_bf16_f32 v34, v116, v119
	v_cvt_pk_bf16_f32 v35, v123, v125
	v_cvt_pk_bf16_f32 v36, v136, v138
	v_cvt_pk_bf16_f32 v37, v141, v142
	s_mov_b32 s71, s67
	s_movk_i32 s8, 0x1000
	v_mfma_f32_32x32x16_bf16 v[18:33], v[66:69], v[34:37], v[18:33]
	v_cvt_pk_bf16_f32 v38, v114, v115
	v_cvt_pk_bf16_f32 v39, v117, v121
	v_cvt_pk_bf16_f32 v40, v124, v127
	v_cvt_pk_bf16_f32 v41, v129, v137
	v_lshl_add_u32 v200, v87, 2, 0
	v_add_u32_e32 v199, 0xa800, v200
	s_add_i32 s17, 0, 0x1c000
	v_mfma_f32_32x32x16_bf16 v[2:17], v[70:73], v[34:37], v[2:17]
	v_cvt_pk_bf16_f32 v34, v120, v122
	v_cvt_pk_bf16_f32 v35, v126, v128
	v_cvt_pk_bf16_f32 v36, v139, v140
	v_cvt_pk_bf16_f32 v37, v143, v144
	s_nop 1
	v_mfma_f32_32x32x16_bf16 v[18:33], v[74:77], v[34:37], v[18:33]
	v_mfma_f32_32x32x16_bf16 v[2:17], v[78:81], v[34:37], v[2:17]
	v_cvt_pk_bf16_f32 v34, v90, v91
	v_cvt_pk_bf16_f32 v35, v92, v93
	v_cvt_pk_bf16_f32 v36, v94, v95
	v_cvt_pk_bf16_f32 v37, v96, v97
	s_nop 1
	v_mfma_f32_32x32x16_bf16 v[18:33], v[62:65], v[34:37], v[18:33]
	v_mfma_f32_32x32x16_bf16 v[2:17], v[58:61], v[34:37], v[2:17]
	v_lshl_add_u64 v[34:35], v[82:83], 0, s[70:71]
	v_add_co_u32_e32 v36, vcc, s8, v34
	s_nop 1
	v_addc_co_u32_e32 v37, vcc, 0, v35, vcc
	v_mfma_f32_32x32x16_bf16 v[18:33], v[54:57], v[38:41], v[18:33]
	s_waitcnt vmcnt(0)
	v_add_u32_e32 v249, 0x21300, v200
	ds_write_b32 v249, v248
	v_lshlrev_b32_e32 v36, 16, v246
	v_mul_f32_e32 v36, 0xbfb8aa3b, v36
	v_exp_f32_e32 v36, v36
	v_mfma_f32_32x32x16_bf16 v[2:17], v[50:53], v[38:41], v[2:17]
	s_nop 6
	v_mul_f32_e64 v32, v0, v32
	v_mul_f32_e64 v33, v0, v33
	v_mul_f32_e64 v30, v0, v30
	v_mul_f32_e64 v31, v0, v31
	v_add_f32_e32 v36, 1.0, v36
	v_div_scale_f32 v37, s[8:9], v36, v36, 1.0
	v_rcp_f32_e32 v38, v37
	v_mul_f32_e32 v28, v0, v28
	v_mul_f32_e32 v29, v0, v29
	v_mul_f32_e32 v26, v0, v26
	v_mul_f32_e32 v27, v0, v27
	v_mul_f32_e32 v24, v0, v24
	v_mul_f32_e32 v25, v0, v25
	v_fma_f32 v39, -v37, v38, 1.0
	v_mul_f32_e32 v22, v0, v22
	v_mul_f32_e32 v23, v0, v23
	v_mul_f32_e32 v20, v0, v20
	v_mul_f32_e32 v21, v0, v21
	v_mul_f32_e32 v18, v0, v18
	v_mul_f32_e32 v19, v0, v19
	v_mul_f32_e32 v16, v0, v16
	v_mul_f32_e32 v17, v0, v17
	v_mul_f32_e32 v14, v0, v14
	v_mul_f32_e32 v15, v0, v15
	v_mul_f32_e32 v12, v0, v12
	v_mul_f32_e32 v13, v0, v13
	v_mul_f32_e32 v10, v0, v10
	v_mul_f32_e32 v11, v0, v11
	v_mul_f32_e32 v8, v0, v8
	v_mul_f32_e32 v9, v0, v9
	v_mul_f32_e32 v6, v0, v6
	v_mul_f32_e32 v7, v0, v7
	v_mul_f32_e32 v4, v0, v4
	v_mul_f32_e32 v5, v0, v5
	v_mul_f32_e32 v2, v0, v2
	v_mul_f32_e32 v3, v0, v3
	v_div_scale_f32 v0, vcc, 1.0, v36, 1.0
	v_fmac_f32_e32 v38, v39, v38
	v_mul_f32_e32 v39, v0, v38
	v_fma_f32 v40, -v37, v39, v0
	v_fmac_f32_e32 v39, v40, v38
	v_fma_f32 v0, -v37, v39, v0
	v_div_fmas_f32 v0, v0, v38, v39
	v_div_fixup_f32 v0, v0, v36, 1.0
	v_mul_f32_e32 v18, v18, v0
	v_mul_f32_e32 v19, v19, v0
	v_mul_f32_e32 v3, v3, v0
	v_mul_f32_e32 v5, v5, v0
	v_mul_f32_e32 v20, v20, v0
	v_mul_f32_e32 v4, v4, v0
	v_mul_f32_e32 v21, v21, v0
	v_mul_f32_e32 v22, v22, v0
	v_mul_f32_e32 v6, v6, v0
	v_mul_f32_e32 v23, v23, v0
	v_mul_f32_e32 v7, v7, v0
	v_mul_f32_e32 v24, v24, v0
	v_mul_f32_e32 v8, v8, v0
	v_mul_f32_e32 v25, v25, v0
	v_mul_f32_e32 v9, v9, v0
	v_mul_f32_e32 v26, v26, v0
	v_mul_f32_e32 v10, v10, v0
	v_mul_f32_e32 v27, v27, v0
	v_mul_f32_e32 v11, v11, v0
	v_mul_f32_e32 v28, v28, v0
	v_mul_f32_e32 v12, v12, v0
	v_mul_f32_e32 v29, v29, v0
	v_mul_f32_e32 v13, v13, v0
	v_mul_f32_e32 v30, v30, v0
	v_mul_f32_e32 v14, v14, v0
	ds_write2st64_b32 v200, v18, v19 offset0:168 offset1:176
	ds_write2st64_b32 v199, v3, v4 offset0:136 offset1:144
	ds_write2st64_b32 v200, v20, v21 offset0:184 offset1:192
	ds_write2st64_b32 v199, v5, v6 offset0:152 offset1:160
	ds_write2st64_b32 v200, v22, v23 offset0:200 offset1:208
	ds_write2st64_b32 v199, v7, v8 offset0:168 offset1:176
	ds_write2st64_b32 v200, v24, v25 offset0:216 offset1:224
	ds_write2st64_b32 v199, v9, v10 offset0:184 offset1:192
	ds_write2st64_b32 v200, v26, v27 offset0:232 offset1:240
	ds_write_b32 v200, v28 offset:63488
	ds_write2st64_b32 v199, v11, v12 offset0:200 offset1:208
	ds_write2st64_b32 v199, v29, v30 offset0:88 offset1:96
	ds_write2st64_b32 v199, v13, v14 offset0:216 offset1:224
	v_mul_f32_e32 v3, v31, v0
	v_mul_f32_e32 v5, v32, v0
	v_mul_f32_e32 v4, v15, v0
	ds_write2st64_b32 v199, v3, v5 offset0:104 offset1:112
	v_mul_f32_e32 v3, v16, v0
	v_mul_f32_e32 v2, v2, v0
	ds_write2st64_b32 v199, v4, v3 offset0:232 offset1:240
	v_mul_f32_e32 v3, v33, v0
	v_mul_f32_e32 v0, v17, v0
	ds_write_b32 v199, v0 offset:63488
	v_and_b32_e32 v0, 15, v84
	v_lshlrev_b32_e32 v8, 2, v0
	ds_write2st64_b32 v199, v3, v2 offset0:120 offset1:128
	v_ashrrev_i32_e32 v6, 4, v87
	s_movk_i32 s8, 0x204
	v_add_u32_e32 v2, -1, v8
	v_cmp_eq_u32_e32 vcc, 0, v0
	v_mul_lo_u32 v3, v6, s8
	v_add_u32_e32 v5, s17, v3
	v_cndmask_b32_e64 v7, v2, 0, vcc
	v_or_b32_e32 v2, 3, v8
	v_mov_b32_e32 v4, 0
	v_cmp_le_i32_e64 s[8:9], v7, v2
	v_mov_b32_e32 v9, 0
	s_waitcnt lgkmcnt(0)
	s_barrier
	s_and_saveexec_b64 s[10:11], s[8:9]
	s_cbranch_execz .LBB0_1426
	v_sub_u32_e32 v9, v8, v7
	v_add_u32_e32 v10, 4, v9
	v_cmp_lt_u32_e64 s[8:9], 1, v10
	s_mov_b64 s[14:15], -1
	v_mov_b32_e32 v9, 0
	s_and_saveexec_b64 s[12:13], s[8:9]
	s_cbranch_execz .LBB0_1421
	v_and_b32_e32 v11, -2, v10
	v_lshl_add_u32 v12, v7, 2, v5
	v_mov_b32_e32 v9, 0
	s_mov_b64 s[14:15], 0
	v_mov_b32_e32 v14, v11
	v_mov_b32_e32 v13, 0

.LBB0_1539:
	s_nop 1
	v_mov_b32_e32 v50, v9
	s_sub_i32 s8, 0x5e0, s7
	s_sub_i32 s16, 0x7ff, s7
	s_max_i32 s8, s8, -1
	s_ashr_i32 s9, s16, 6
	s_add_i32 s8, s8, 1
	s_add_i32 s10, s9, 1
	s_lshr_b32 s11, s8, 6
	s_lshl_b32 s8, -1, s10
	s_not_b32 s8, s8
	s_cmp_lg_u32 s9, 31
	v_mov_b32_e32 v51, v10
	s_cselect_b32 s10, s8, -1
	v_mov_b32_e32 v56, v12
	ds_read2st64_b32 v[34:35], v200 offset0:168 offset1:176
	ds_read2st64_b32 v[138:139], v199 offset0:120 offset1:128
	ds_read2st64_b32 v[36:37], v199 offset0:136 offset1:144
	ds_read2st64_b32 v[38:39], v200 offset0:184 offset1:192
	ds_read2st64_b32 v[40:41], v199 offset0:152 offset1:160
	ds_read2st64_b32 v[42:43], v200 offset0:200 offset1:208
	ds_read2st64_b32 v[44:45], v199 offset0:168 offset1:176
	ds_read2st64_b32 v[46:47], v200 offset0:216 offset1:224
	ds_read2st64_b32 v[48:49], v199 offset0:184 offset1:192
	ds_read2st64_b32 v[140:141], v200 offset0:232 offset1:240
	ds_read2st64_b32 v[54:55], v199 offset0:200 offset1:208
	v_mov_b32_e32 v57, v28
	ds_read2st64_b32 v[142:143], v199 offset0:88 offset1:96
	ds_read2st64_b32 v[144:145], v199 offset0:216 offset1:224
	ds_read2st64_b32 v[146:147], v199 offset0:104 offset1:112
	ds_read2st64_b32 v[148:149], v199 offset0:232 offset1:240
	ds_read_b32 v59, v200 offset:63488
	ds_read_b32 v219, v199 offset:63488
	s_lshl_b32 s11, -1, s11
	s_waitcnt lgkmcnt(7)
	v_mov_b32_e32 v61, v141
	s_waitcnt lgkmcnt(6)
	v_mov_b32_e32 v60, v54
	v_mov_b32_e32 v58, v55
	s_waitcnt vmcnt(0)
	v_lshlrev_b32_e32 v9, 16, v247
	v_mul_f32_e32 v9, 0xbfb8aa3b, v9
	v_exp_f32_e32 v9, v9
	s_nop 0
	v_add_f32_e32 v9, 1.0, v9
	v_div_scale_f32 v10, s[8:9], v9, v9, 1.0
	v_rcp_f32_e32 v12, v10
	v_div_scale_f32 v28, vcc, 1.0, v9, 1.0
	v_fma_f32 v53, -v10, v12, 1.0
	v_fmac_f32_e32 v12, v53, v12
	v_mul_f32_e32 v53, v28, v12
	v_fma_f32 v54, -v10, v53, v28
	v_fmac_f32_e32 v53, v54, v12
	v_fma_f32 v10, -v10, v53, v28
	v_div_fmas_f32 v10, v10, v12, v53
	v_div_fixup_f32 v9, v10, v9, 1.0
	v_div_scale_f32 v10, s[8:9], v52, v52, v9
	v_rcp_f32_e32 v12, v10
	v_div_scale_f32 v28, vcc, v9, v52, v9
	s_and_b32 s9, s11, s10
	v_fma_f32 v53, -v10, v12, 1.0
	v_fmac_f32_e32 v12, v53, v12
	v_mul_f32_e32 v53, v28, v12
	v_fma_f32 v54, -v10, v53, v28
	v_fmac_f32_e32 v53, v54, v12
	v_fma_f32 v10, -v10, v53, v28
	v_div_fmas_f32 v10, v10, v12, v53
	v_div_fixup_f32 v10, v10, v52, v9
	v_fmac_f32_e32 v140, v26, v10
	v_mov_b32_e32 v26, v11
	v_fma_f32 v9, v18, v10, v34
	v_fma_f32 v2, v2, v10, v139
	v_fmac_f32_e32 v35, v19, v10
	v_fma_f32 v150, v50, v10, v48
	v_fma_f32 v151, v51, v10, v49
	s_waitcnt lgkmcnt(1)
	v_fma_f32 v152, v56, v10, v58
	v_fma_f32 v153, v57, v10, v59
	v_fma_f32 v139, v29, v10, v142
	v_fma_f32 v141, v13, v10, v144
	v_fmac_f32_e32 v143, v30, v10
	v_fmac_f32_e32 v145, v14, v10
	v_fma_f32 v142, v31, v10, v146
	v_fma_f32 v144, v15, v10, v148
	v_fmac_f32_e32 v147, v32, v10
	v_fmac_f32_e32 v149, v16, v10
	v_fmac_f32_e32 v138, v33, v10
	s_waitcnt lgkmcnt(0)
	v_fmac_f32_e32 v219, v17, v10
	v_fma_f32 v154, v26, v10, v60
	v_fma_f32 v155, v27, v10, v61
	s_cmp_lg_u32 s9, 0
	v_fma_f32 v3, v3, v10, v36
	v_fma_f32 v12, v20, v10, v38
	v_fmac_f32_e32 v37, v4, v10
	v_fmac_f32_e32 v39, v21, v10
	v_fma_f32 v4, v5, v10, v40
	v_fma_f32 v5, v22, v10, v42
	v_fmac_f32_e32 v41, v6, v10
	v_fmac_f32_e32 v43, v23, v10
	v_fma_f32 v6, v7, v10, v44
	v_fma_f32 v7, v24, v10, v46
	v_fmac_f32_e32 v45, v8, v10
	v_fmac_f32_e32 v47, v25, v10
	ds_write2st64_b32 v200, v9, v35 offset0:168 offset1:176
	ds_write2st64_b32 v199, v3, v37 offset0:136 offset1:144
	ds_write2st64_b32 v200, v12, v39 offset0:184 offset1:192
	ds_write2st64_b32 v199, v4, v41 offset0:152 offset1:160
	ds_write2st64_b32 v200, v5, v43 offset0:200 offset1:208
	ds_write2st64_b32 v199, v6, v45 offset0:168 offset1:176
	ds_write2st64_b32 v200, v7, v47 offset0:216 offset1:224
	ds_write2st64_b32 v199, v150, v151 offset0:184 offset1:192
	ds_write_b32 v200, v153 offset:63488
	ds_write2st64_b32 v199, v139, v143 offset0:88 offset1:96
	ds_write2st64_b32 v199, v141, v145 offset0:216 offset1:224
	ds_write2st64_b32 v199, v142, v147 offset0:104 offset1:112
	ds_write2st64_b32 v199, v144, v149 offset0:232 offset1:240
	ds_write2st64_b32 v199, v138, v2 offset0:120 offset1:128
	ds_write2st64_b32 v200, v140, v155 offset0:232 offset1:240
	ds_write2st64_b32 v199, v154, v152 offset0:200 offset1:208
	ds_write_b32 v199, v219 offset:63488
	s_cbranch_scc0 .LBB0_1618
	s_add_u32 s8, s20, s46
	s_addc_u32 s13, s21, 0
	s_add_u32 s10, s8, 0x1700
	s_addc_u32 s11, s13, 0
	s_add_u32 s12, s8, 0x1600
	s_addc_u32 s13, s13, 0
	s_ff1_i32_b32 s8, s9
	s_add_i32 s14, s9, -1
	s_and_b32 s9, s14, s9
	s_mul_i32 s17, s8, 0x68000
	s_add_u32 s14, s12, s17
	s_addc_u32 s15, s13, 0
	global_load_dwordx4 v[2:5], v0, s[14:15]
	s_add_u32 s14, s10, s17
	s_addc_u32 s15, s11, 0
	global_load_dwordx4 v[6:9], v0, s[14:15]
	v_mov_b32_e32 v10, v1
	v_mov_b32_e32 v11, v1
	v_mov_b32_e32 v12, v1
	v_mov_b32_e32 v13, v1
	v_mov_b32_e32 v14, v1
	v_mov_b32_e32 v15, v1
	v_mov_b32_e32 v16, v1
	v_mov_b32_e32 v17, v1
	v_mov_b32_e32 v18, v1
	v_mov_b32_e32 v19, v1
	v_mov_b32_e32 v20, v1
	v_mov_b32_e32 v21, v1
	v_mov_b32_e32 v22, v1
	v_mov_b32_e32 v23, v1
	v_mov_b32_e32 v24, v1
	v_mov_b32_e32 v25, v1
	v_mov_b32_e32 v26, v1
	v_mov_b32_e32 v27, v1
	v_mov_b32_e32 v28, v1
	v_mov_b32_e32 v29, v1
	v_mov_b32_e32 v30, v1
	v_mov_b32_e32 v31, v1
	v_lshl_add_u64 v[156:157], s[10:11], 0, v[0:1]
	v_mov_b32_e32 v146, 0
	s_mov_b32 s17, 0
	s_addk_i32 s7, 0xf85e
	v_mov_b32_e32 v148, 0xf149f2ca
	v_mov_b32_e32 v158, 0
	v_mov_b32_e32 v159, v146
	v_mov_b32_e32 v160, 0
	v_mov_b32_e32 v161, v146
	v_mov_b32_e32 v162, 0
	v_mov_b32_e32 v163, v146
	v_mov_b32_e32 v164, 0
	v_mov_b32_e32 v165, v146
	v_mov_b32_e32 v166, 0
	v_mov_b32_e32 v167, v146
	v_mov_b32_e32 v168, 0
	v_mov_b32_e32 v169, v146
	v_mov_b32_e32 v170, 0
	v_mov_b32_e32 v171, v146
	v_mov_b32_e32 v172, 0
	v_mov_b32_e32 v173, v146
	v_mov_b32_e32 v174, 0
	v_mov_b32_e32 v175, v146
	v_mov_b32_e32 v176, 0
	v_mov_b32_e32 v177, v146
	v_mov_b32_e32 v178, 0
	v_mov_b32_e32 v179, v146
	v_mov_b32_e32 v180, 0
	v_mov_b32_e32 v181, v146
	v_mov_b32_e32 v182, 0
	v_mov_b32_e32 v183, v146
	v_mov_b32_e32 v184, 0
	v_mov_b32_e32 v185, v146
	v_mov_b32_e32 v186, 0
	v_mov_b32_e32 v187, v146
	v_mov_b32_e32 v188, 0
	v_mov_b32_e32 v189, v146
	s_mov_b32 s18, s8
	s_waitcnt vmcnt(1)
	ds_write_b128 v135, v[2:5]
	s_waitcnt vmcnt(0)
	ds_write_b128 v134, v[6:9] offset:9216
	v_mov_b32_e32 v2, v1
	v_mov_b32_e32 v3, v1
	v_mov_b32_e32 v4, v1
	v_mov_b32_e32 v5, v1
	v_mov_b32_e32 v6, v1
	v_mov_b32_e32 v7, v1
	v_mov_b32_e32 v8, v1
	v_mov_b32_e32 v9, v1
	v_lshl_add_u64 v[134:135], s[12:13], 0, v[0:1]
	v_mov_b32_e32 v0, v1
	v_mov_b64_e32 v[32:33], v[30:31]
	v_mov_b64_e32 v[30:31], v[28:29]
	v_mov_b64_e32 v[28:29], v[26:27]
	v_mov_b64_e32 v[26:27], v[24:25]
	v_mov_b64_e32 v[24:25], v[22:23]
	v_mov_b64_e32 v[22:23], v[20:21]
	v_mov_b64_e32 v[20:21], v[18:19]
	v_mov_b64_e32 v[18:19], v[16:17]
	v_mov_b64_e32 v[16:17], v[14:15]
	v_mov_b64_e32 v[14:15], v[12:13]
	v_mov_b64_e32 v[12:13], v[10:11]
	v_mov_b64_e32 v[10:11], v[8:9]
	v_mov_b64_e32 v[8:9], v[6:7]
	v_mov_b64_e32 v[6:7], v[4:5]
	v_mov_b64_e32 v[4:5], v[2:3]
	v_mov_b64_e32 v[2:3], v[0:1]
	s_waitcnt lgkmcnt(0)
	s_barrier
